# SSD-B item prologue staging loop: both loads of an iteration issued together with one wait
# speedup vs baseline: 1.0070x; 1.0012x over previous
.LBB0_928:
	v_add_co_u32_e32 v8, vcc, 0x90000, v4
	v_add_u32_e32 v7, 0xfffff000, v6
	s_nop 0
	v_addc_co_u32_e32 v9, vcc, 0, v5, vcc
	global_load_dword v3, v[8:9], off
	global_load_dword v10, v[4:5], off
	v_add_u32_e32 v0, 0x200, v0
	v_cmp_lt_i32_e32 vcc, s4, v0
	s_or_b64 s[14:15], vcc, s[14:15]
	v_lshl_add_u64 v[4:5], v[4:5], 0, s[20:21]
	s_waitcnt vmcnt(0) lgkmcnt(0)
	ds_write_b32 v7, v3
	ds_write_b32 v6, v10
	v_add_u32_e32 v6, 0x800, v6
	s_andn2_b64 exec, exec, s[14:15]
	s_cbranch_execnz .LBB0_928
